# v39 plus scalar wave-uniform causal test in the prompt attention loop (strategy 7.12)
# speedup vs baseline: 1.0052x; 1.0041x over previous
; #define AT_GLOAD(kt_) do { r0 = *(const u32x4v*)(KNb + (size_t)(kt_) * 64 * 512); \
;                 if (lo) { r1 = *(const u32x4v*)(KRb + (size_t)(kt_) * 64 * 32); r2 = *(const u32x4v*)(VTb + (kt_) * 64); } \
;                 else { r1 = *(const u32x4v*)(VTb + (kt_) * 64); } } while (0)
; #define AT_LSTORE(bf_) do { PG8_LAS unsigned char* bb_ = lds + (bf_) * BUF; *(PG8_LAS u32x4v*)(bb_ + k_st) = r0; \
;                 if (lo) { *(PG8_LAS u32x4v*)(bb_ + r_st) = r1; *(PG8_LAS u32x4v*)(bb_ + v_st) = r2; } else { *(PG8_LAS u32x4v*)(bb_ + v_st) = r1; } } while (0)
; __device__ void phase_attn(KP p, PG8_LAS unsigned char* lds, float* ldsf, int tid_in) {
;     ...
;             const int qw = qb * 8 + (7 - wid), cw = qw >> 1, nt = 4 * qb + 4;
;             const bf16_t* Qw = Q + (kr0 + (size_t)qw * 32) * 768 + h * 96;
;             bf16x8 qf[3][2];
; #pragma unroll
;             for (int ks = 0; ks < 3; ++ks)
; #pragma unroll
;                 for (int nb = 0; nb < 2; ++nb) qf[ks][nb] = *(const bf16x8*)(Qw + (size_t)(nb * 16 + fr) * 768 + ks * 32 + g * 8);
;             f32x4 o[4][2]; float mrun[2], lrun[2];
; #pragma unroll
;             for (int nb = 0; nb < 2; ++nb) { mrun[nb] = -1e30f; lrun[nb] = 0.f;
; #pragma unroll
;                 for (int df = 0; df < 4; ++df) o[df][nb] = (f32x4){0.f, 0.f, 0.f, 0.f}; }
;             u32x4v r0, r1, r2;
;     ...
;             AT_GLOAD(0); AT_LSTORE(0); __syncthreads();
.LBB0_516:
	s_or_b64 exec, exec, s[8:9]
	v_add_u32_e32 v4, 0, v166
	v_mov_b32_e32 v18, v9
	v_mov_b32_e32 v19, v9
	v_mov_b32_e32 v20, v9
	v_mov_b32_e32 v21, v9
	v_ashrrev_i32_e32 v171, 1, v14
	s_nop 0
	v_readfirstlane_b32 s36, v171
	s_waitcnt vmcnt(0)
	ds_write_b128 v4, v[10:13] offset:13312
	v_mov_b32_e32 v8, v9
	v_mov_b64_e32 v[68:69], v[20:21]
	v_mov_b64_e32 v[14:15], v[18:19]
	v_mov_b64_e32 v[64:65], v[20:21]
	v_mov_b64_e32 v[10:11], v[18:19]
	v_mov_b64_e32 v[60:61], v[20:21]
	v_mov_b64_e32 v[4:5], v[18:19]
	v_mov_b64_e32 v[56:57], v[20:21]
	s_mov_b32 s12, 0
	v_mov_b32_e32 v132, 0xf149f2ca
	v_mov_b32_e32 v226, 0
	v_mov_b32_e32 v227, 0
	v_mov_b32_e32 v228, 0
	v_mov_b32_e32 v229, 0
	v_mov_b32_e32 v230, 0
	v_mov_b32_e32 v231, 0
	v_mov_b32_e32 v232, 0
	v_mov_b32_e32 v233, 0
	v_mov_b64_e32 v[128:129], v[120:121]
	v_mov_b64_e32 v[130:131], v[118:119]
	v_mov_b64_e32 v[66:67], v[18:19]
	v_mov_b64_e32 v[16:17], v[20:21]
	v_mov_b64_e32 v[62:63], v[18:19]
	v_mov_b64_e32 v[12:13], v[20:21]
	v_mov_b64_e32 v[58:59], v[18:19]
	v_mov_b64_e32 v[6:7], v[20:21]
	v_mov_b64_e32 v[54:55], v[18:19]
	v_mov_b32_e32 v74, 0xf149f2ca
	v_mov_b64_e32 v[124:125], v[8:9]
	s_waitcnt lgkmcnt(0)
	s_barrier

; __device__ void phase_attn(KP p, PG8_LAS unsigned char* lds, float* ldsf, int tid_in) {
;     ...
;             for (int kt = 0; kt < nt; ++kt) {
;                 if (kt + 1 < nt) AT_GLOAD(kt + 1);
;                 if (kt <= cw) {
;                     const PG8_LAS unsigned char* kb = lds + (kt & 1) * BUF;
;                     f32x4 st[4][2];
; #pragma unroll
;                     for (int f = 0; f < 4; ++f) {
;                         const bf16x8 a0 = *(const PG8_LAS bf16x8*)(kb + ka_rd + f * 16 * KS * 2);
;                         const bf16x8 a1 = *(const PG8_LAS bf16x8*)(kb + ka_rd + f * 16 * KS * 2 + 64);
;                         const bf16x8 a2 = *(const PG8_LAS bf16x8*)(kb + ka_rd + f * 16 * KS * 2 + 128);
; #pragma unroll
;                         for (int nb = 0; nb < 2; ++nb) {
;                             f32x4 c = {0.f, 0.f, 0.f, 0.f};
;                             c = __builtin_amdgcn_mfma_f32_16x16x32_bf16(a0, qf[0][nb], c, 0, 0, 0);
;                             c = __builtin_amdgcn_mfma_f32_16x16x32_bf16(a1, qf[1][nb], c, 0, 0, 0);
;                             c = __builtin_amdgcn_mfma_f32_16x16x32_bf16(a2, qf[2][nb], c, 0, 0, 0);
;                             st[f][nb] = c;
;                         }
;                     }
; #pragma unroll
;                     for (int nb = 0; nb < 2; ++nb) {
;                         float mx = -1e30f;
; #pragma unroll
;                         for (int f = 0; f < 4; ++f)
; #pragma unroll
;                             for (int r = 0; r < 4; ++r) mx = fmaxf(mx, st[f][nb][r]);
;                         mx = fmaxf(mx, shx(mx, 16, lane)); mx = fmaxf(mx, shx(mx, 32, lane));
;                         const float mn = fmaxf(mrun[nb], mx), al = __builtin_amdgcn_exp2f(mrun[nb] - mn); mrun[nb] = mn;
;                         float ps = 0.f;
; #pragma unroll
;                         for (int f = 0; f < 4; ++f)
; #pragma unroll
;                             for (int r = 0; r < 4; ++r) { const float e = __builtin_amdgcn_exp2f(st[f][nb][r] - mn); st[f][nb][r] = e; ps += e; }
;                         lrun[nb] = lrun[nb] * al + ps;
; #pragma unroll
;                         for (int df = 0; df < 4; ++df) o[df][nb] *= al;
;                     }
; #pragma unroll
;                     for (int kk = 0; kk < 2; ++kk) {
;                         bf16x8 pb[2];
; #pragma unroll
.LBB0_519:
	s_or_b64 exec, exec, s[8:9]
	global_load_dwordx4 v[50:53], v[50:51], off
	s_mov_b64 s[8:9], exec
	s_cmp_le_i32 s12, s36
	s_cbranch_scc0 .LBB0_521
	s_bitcmp1_b32 s12, 0
	s_cselect_b32 s12, 0x5800, 0
	s_add_i32 s12, s12, 0
	s_cmp_eq_u32 s40, 1
	s_cbranch_scc1 .Lat3_slow_1
	v_add_u32_e32 v8, s12, v167
	ds_read_b128 v[178:181], v8
	ds_read_b128 v[182:185], v8 offset:64
	ds_read_b128 v[186:189], v8 offset:128
	ds_read_b128 v[190:193], v8 offset:3328
	ds_read_b128 v[194:197], v8 offset:3392
	ds_read_b128 v[198:201], v8 offset:3456
	ds_read_b128 v[202:205], v8 offset:6656
	ds_read_b128 v[206:209], v8 offset:6720
	ds_read_b128 v[210:213], v8 offset:6784
	ds_read_b128 v[214:217], v8 offset:9984
	ds_read_b128 v[218:221], v8 offset:10048
	ds_read_b128 v[222:225], v8 offset:10112
	v_add_u32_e32 v92, s12, v170
	s_waitcnt lgkmcnt(9)
	v_mfma_f32_16x16x32_bf16 v[134:137], v[178:181], v[22:25], v[226:229]
	v_mfma_f32_16x16x32_bf16 v[134:137], v[182:185], v[26:29], v[134:137]
	v_mfma_f32_16x16x32_bf16 v[134:137], v[186:189], v[38:41], v[134:137]
	s_waitcnt lgkmcnt(6)
	v_mfma_f32_16x16x32_bf16 v[138:141], v[190:193], v[22:25], v[226:229]
	v_mfma_f32_16x16x32_bf16 v[138:141], v[194:197], v[26:29], v[138:141]
	v_mfma_f32_16x16x32_bf16 v[138:141], v[198:201], v[38:41], v[138:141]
	s_waitcnt lgkmcnt(3)
	v_mfma_f32_16x16x32_bf16 v[142:145], v[202:205], v[22:25], v[226:229]
	v_mfma_f32_16x16x32_bf16 v[142:145], v[206:209], v[26:29], v[142:145]
	v_mfma_f32_16x16x32_bf16 v[142:145], v[210:213], v[38:41], v[142:145]
	s_waitcnt lgkmcnt(0)
	v_mfma_f32_16x16x32_bf16 v[146:149], v[214:217], v[22:25], v[226:229]
	v_mfma_f32_16x16x32_bf16 v[146:149], v[218:221], v[26:29], v[146:149]
	v_mfma_f32_16x16x32_bf16 v[146:149], v[222:225], v[38:41], v[146:149]
	v_mfma_f32_16x16x32_bf16 v[76:79], v[178:181], v[42:45], v[230:233]
	v_mfma_f32_16x16x32_bf16 v[76:79], v[182:185], v[30:33], v[76:79]
	v_mfma_f32_16x16x32_bf16 v[76:79], v[186:189], v[34:37], v[76:79]
	v_exp_f32_e32 v134, v134
	v_exp_f32_e32 v135, v135
	v_mfma_f32_16x16x32_bf16 v[80:83], v[190:193], v[42:45], v[230:233]
	v_exp_f32_e32 v136, v136
	v_exp_f32_e32 v137, v137
	v_mfma_f32_16x16x32_bf16 v[80:83], v[194:197], v[30:33], v[80:83]
	v_exp_f32_e32 v138, v138
	v_exp_f32_e32 v139, v139
	v_mfma_f32_16x16x32_bf16 v[80:83], v[198:201], v[34:37], v[80:83]
	v_exp_f32_e32 v140, v140
	v_exp_f32_e32 v141, v141
	v_mfma_f32_16x16x32_bf16 v[84:87], v[202:205], v[42:45], v[230:233]
	v_exp_f32_e32 v142, v142
	v_exp_f32_e32 v143, v143
	v_mfma_f32_16x16x32_bf16 v[84:87], v[206:209], v[30:33], v[84:87]
	v_exp_f32_e32 v144, v144
	v_exp_f32_e32 v145, v145
	v_mfma_f32_16x16x32_bf16 v[84:87], v[210:213], v[34:37], v[84:87]
	v_exp_f32_e32 v146, v146
	v_exp_f32_e32 v147, v147
	v_mfma_f32_16x16x32_bf16 v[88:91], v[214:217], v[42:45], v[230:233]
	v_exp_f32_e32 v148, v148
	v_exp_f32_e32 v149, v149
	v_mfma_f32_16x16x32_bf16 v[88:91], v[218:221], v[30:33], v[88:91]
	v_mfma_f32_16x16x32_bf16 v[88:91], v[222:225], v[34:37], v[88:91]
	ds_read_b64 v[178:179], v92 offset:13312
	ds_read_b64 v[180:181], v92 offset:13344
	ds_read_b64 v[182:183], v92 offset:15616
	ds_read_b64 v[184:185], v92 offset:15648
	ds_read_b64 v[186:187], v92 offset:17920
	ds_read_b64 v[188:189], v92 offset:17952
	ds_read_b64 v[190:191], v92 offset:20224
	ds_read_b64 v[192:193], v92 offset:20256
	ds_read_b64 v[194:195], v92 offset:13376
	ds_read_b64 v[196:197], v92 offset:13408
	ds_read_b64 v[198:199], v92 offset:15680
	ds_read_b64 v[200:201], v92 offset:15712
	ds_read_b64 v[202:203], v92 offset:17984
	ds_read_b64 v[204:205], v92 offset:18016
	ds_read_b64 v[206:207], v92 offset:20288
	ds_read_b64 v[208:209], v92 offset:20320
	v_exp_f32_e32 v76, v76
	v_exp_f32_e32 v77, v77
	v_exp_f32_e32 v78, v78
	v_exp_f32_e32 v79, v79
	v_exp_f32_e32 v80, v80
	v_exp_f32_e32 v81, v81
	v_exp_f32_e32 v82, v82
	v_exp_f32_e32 v83, v83
	v_exp_f32_e32 v84, v84
	v_exp_f32_e32 v85, v85
	v_exp_f32_e32 v86, v86
	v_exp_f32_e32 v87, v87
	v_exp_f32_e32 v88, v88
	v_exp_f32_e32 v89, v89
	v_exp_f32_e32 v90, v90
	v_exp_f32_e32 v91, v91
	v_pk_add_f32 v[162:163], v[134:135], v[136:137]
	v_pk_add_f32 v[174:175], v[138:139], v[140:141]
	v_pk_add_f32 v[162:163], v[162:163], v[142:143]
	v_pk_add_f32 v[174:175], v[174:175], v[144:145]
	v_pk_add_f32 v[162:163], v[162:163], v[146:147]
	v_pk_add_f32 v[174:175], v[174:175], v[148:149]
	v_pk_add_f32 v[162:163], v[162:163], v[174:175]
	v_add_f32_e32 v154, v162, v163
	v_pk_add_f32 v[176:177], v[76:77], v[78:79]
	v_pk_add_f32 v[70:71], v[80:81], v[82:83]
	v_pk_add_f32 v[176:177], v[176:177], v[84:85]
	v_pk_add_f32 v[70:71], v[70:71], v[86:87]
	v_pk_add_f32 v[176:177], v[176:177], v[88:89]
	v_pk_add_f32 v[70:71], v[70:71], v[90:91]
	v_pk_add_f32 v[176:177], v[176:177], v[70:71]
	v_add_f32_e32 v155, v176, v177
	v_max_f32_e32 v156, v154, v155
	v_cmp_ngt_f32_e32 vcc, 0x45800000, v156
	v_cvt_pk_bf16_f32 v134, v134, v135
	v_cvt_pk_bf16_f32 v135, v136, v137
	v_cvt_pk_bf16_f32 v136, v138, v139
	v_cvt_pk_bf16_f32 v137, v140, v141
	s_and_b64 vcc, exec, vcc
	s_cbranch_vccnz .Lat3_slowq_1
	v_add_f32_e32 v125, v125, v154
	v_add_f32_e32 v124, v124, v155
	v_cvt_pk_bf16_f32 v142, v142, v143
	v_cvt_pk_bf16_f32 v143, v144, v145
	v_cvt_pk_bf16_f32 v144, v146, v147
	v_cvt_pk_bf16_f32 v145, v148, v149
	s_waitcnt lgkmcnt(8)
	v_mfma_f32_16x16x32_bf16 v[54:57], v[178:181], v[134:137], v[54:57]
	v_cvt_pk_bf16_f32 v76, v76, v77
	v_mfma_f32_16x16x32_bf16 v[58:61], v[182:185], v[134:137], v[58:61]
	v_cvt_pk_bf16_f32 v77, v78, v79
	v_mfma_f32_16x16x32_bf16 v[62:65], v[186:189], v[134:137], v[62:65]
	v_cvt_pk_bf16_f32 v78, v80, v81
	v_mfma_f32_16x16x32_bf16 v[66:69], v[190:193], v[134:137], v[66:69]
	v_cvt_pk_bf16_f32 v79, v82, v83
	s_waitcnt lgkmcnt(0)
	v_mfma_f32_16x16x32_bf16 v[54:57], v[194:197], v[142:145], v[54:57]
	v_cvt_pk_bf16_f32 v84, v84, v85
	v_mfma_f32_16x16x32_bf16 v[58:61], v[198:201], v[142:145], v[58:61]
	v_cvt_pk_bf16_f32 v85, v86, v87
	v_mfma_f32_16x16x32_bf16 v[62:65], v[202:205], v[142:145], v[62:65]
	v_cvt_pk_bf16_f32 v86, v88, v89
	v_mfma_f32_16x16x32_bf16 v[66:69], v[206:209], v[142:145], v[66:69]
	v_cvt_pk_bf16_f32 v87, v90, v91
	v_mfma_f32_16x16x32_bf16 v[4:7], v[178:181], v[76:79], v[4:7]
	v_mfma_f32_16x16x32_bf16 v[10:13], v[182:185], v[76:79], v[10:13]
	v_mfma_f32_16x16x32_bf16 v[14:17], v[186:189], v[76:79], v[14:17]
	v_mfma_f32_16x16x32_bf16 v[18:21], v[190:193], v[76:79], v[18:21]
	v_mfma_f32_16x16x32_bf16 v[4:7], v[194:197], v[84:87], v[4:7]
	v_mfma_f32_16x16x32_bf16 v[10:13], v[198:201], v[84:87], v[10:13]
	v_mfma_f32_16x16x32_bf16 v[14:17], v[202:205], v[84:87], v[14:17]
	v_mfma_f32_16x16x32_bf16 v[18:21], v[206:209], v[84:87], v[18:21]
	s_branch .Lat3_end_1

; #define PG8_LAS __attribute__((address_space(3)))
; __device__ void phase_attn(KP p, PG8_LAS unsigned char* lds, float* ldsf, int tid_in) {
;     ...
;                 if (kt <= cw) {
;                     const PG8_LAS unsigned char* kb = lds + (kt & 1) * BUF;
;                     f32x4 st[4][2];
; #pragma unroll
;                     for (int f = 0; f < 4; ++f) {
;                         const bf16x8 a0 = *(const PG8_LAS bf16x8*)(kb + ka_rd + f * 16 * KS * 2);
;                         const bf16x8 a1 = *(const PG8_LAS bf16x8*)(kb + ka_rd + f * 16 * KS * 2 + 64);
;                         const bf16x8 a2 = *(const PG8_LAS bf16x8*)(kb + ka_rd + f * 16 * KS * 2 + 128);
; #pragma unroll
;                         for (int nb = 0; nb < 2; ++nb) {
;                             f32x4 c = {0.f, 0.f, 0.f, 0.f};
;                             c = __builtin_amdgcn_mfma_f32_16x16x32_bf16(a0, qf[0][nb], c, 0, 0, 0);
;                             c = __builtin_amdgcn_mfma_f32_16x16x32_bf16(a1, qf[1][nb], c, 0, 0, 0);
;                             c = __builtin_amdgcn_mfma_f32_16x16x32_bf16(a2, qf[2][nb], c, 0, 0, 0);
;                             st[f][nb] = c;
;                         }
;                     }
; #pragma unroll
;                     for (int nb = 0; nb < 2; ++nb) {
;                         float mx = -1e30f;
; #pragma unroll
;                         for (int f = 0; f < 4; ++f)
; #pragma unroll
;                             for (int r = 0; r < 4; ++r) mx = fmaxf(mx, st[f][nb][r]);
;                         mx = fmaxf(mx, shx(mx, 16, lane)); mx = fmaxf(mx, shx(mx, 32, lane));
;                         const float mn = fmaxf(mrun[nb], mx), al = __builtin_amdgcn_exp2f(mrun[nb] - mn); mrun[nb] = mn;
;                         float ps = 0.f;
; #pragma unroll
;                         for (int f = 0; f < 4; ++f)
; #pragma unroll
;                             for (int r = 0; r < 4; ++r) { const float e = __builtin_amdgcn_exp2f(st[f][nb][r] - mn); st[f][nb][r] = e; ps += e; }
;                         lrun[nb] = lrun[nb] * al + ps;
; #pragma unroll
;                         for (int df = 0; df < 4; ++df) o[df][nb] *= al;
;                     }
; #pragma unroll
;                     for (int kk = 0; kk < 2; ++kk) {
;                         bf16x8 pb[2];
; #pragma unroll
;                         for (int nb = 0; nb < 2; ++nb) {
.LBB0_525:
	s_add_i32 s8, s0, -2
	s_cmp_lt_i32 s8, s36
	s_mov_b64 s[8:9], exec
	s_cbranch_scc0 .LBB0_511
	v_add_u32_e32 v8, s12, v167
	ds_read_b128 v[178:181], v8
	ds_read_b128 v[182:185], v8 offset:64
	ds_read_b128 v[186:189], v8 offset:128
	ds_read_b128 v[190:193], v8 offset:3328
	ds_read_b128 v[194:197], v8 offset:3392
	ds_read_b128 v[198:201], v8 offset:3456
	ds_read_b128 v[202:205], v8 offset:6656
	ds_read_b128 v[206:209], v8 offset:6720
	ds_read_b128 v[210:213], v8 offset:6784
	ds_read_b128 v[214:217], v8 offset:9984
	ds_read_b128 v[218:221], v8 offset:10048
	ds_read_b128 v[222:225], v8 offset:10112
	v_add_u32_e32 v92, s12, v170
	s_waitcnt lgkmcnt(9)
	v_mfma_f32_16x16x32_bf16 v[134:137], v[178:181], v[22:25], v[226:229]
	v_mfma_f32_16x16x32_bf16 v[134:137], v[182:185], v[26:29], v[134:137]
	v_mfma_f32_16x16x32_bf16 v[134:137], v[186:189], v[38:41], v[134:137]
	s_waitcnt lgkmcnt(6)
	v_mfma_f32_16x16x32_bf16 v[138:141], v[190:193], v[22:25], v[226:229]
	v_mfma_f32_16x16x32_bf16 v[138:141], v[194:197], v[26:29], v[138:141]
	v_mfma_f32_16x16x32_bf16 v[138:141], v[198:201], v[38:41], v[138:141]
	s_waitcnt lgkmcnt(3)
	v_mfma_f32_16x16x32_bf16 v[142:145], v[202:205], v[22:25], v[226:229]
	v_mfma_f32_16x16x32_bf16 v[142:145], v[206:209], v[26:29], v[142:145]
	v_mfma_f32_16x16x32_bf16 v[142:145], v[210:213], v[38:41], v[142:145]
	s_waitcnt lgkmcnt(0)
	v_mfma_f32_16x16x32_bf16 v[146:149], v[214:217], v[22:25], v[226:229]
	v_mfma_f32_16x16x32_bf16 v[146:149], v[218:221], v[26:29], v[146:149]
	v_mfma_f32_16x16x32_bf16 v[146:149], v[222:225], v[38:41], v[146:149]
	v_mfma_f32_16x16x32_bf16 v[76:79], v[178:181], v[42:45], v[230:233]
	v_mfma_f32_16x16x32_bf16 v[76:79], v[182:185], v[30:33], v[76:79]
	v_mfma_f32_16x16x32_bf16 v[76:79], v[186:189], v[34:37], v[76:79]
	v_exp_f32_e32 v134, v134
	v_exp_f32_e32 v135, v135
	v_mfma_f32_16x16x32_bf16 v[80:83], v[190:193], v[42:45], v[230:233]
	v_exp_f32_e32 v136, v136
	v_exp_f32_e32 v137, v137
	v_mfma_f32_16x16x32_bf16 v[80:83], v[194:197], v[30:33], v[80:83]
	v_exp_f32_e32 v138, v138
	v_exp_f32_e32 v139, v139
	v_mfma_f32_16x16x32_bf16 v[80:83], v[198:201], v[34:37], v[80:83]
	v_exp_f32_e32 v140, v140
	v_exp_f32_e32 v141, v141
	v_mfma_f32_16x16x32_bf16 v[84:87], v[202:205], v[42:45], v[230:233]
	v_exp_f32_e32 v142, v142
	v_exp_f32_e32 v143, v143
	v_mfma_f32_16x16x32_bf16 v[84:87], v[206:209], v[30:33], v[84:87]
	v_exp_f32_e32 v144, v144
	v_exp_f32_e32 v145, v145
	v_mfma_f32_16x16x32_bf16 v[84:87], v[210:213], v[34:37], v[84:87]
	v_exp_f32_e32 v146, v146
	v_exp_f32_e32 v147, v147
	v_mfma_f32_16x16x32_bf16 v[88:91], v[214:217], v[42:45], v[230:233]
	v_exp_f32_e32 v148, v148
	v_exp_f32_e32 v149, v149
	v_mfma_f32_16x16x32_bf16 v[88:91], v[218:221], v[30:33], v[88:91]
	v_mfma_f32_16x16x32_bf16 v[88:91], v[222:225], v[34:37], v[88:91]
	ds_read_b64 v[178:179], v92 offset:13312
	ds_read_b64 v[180:181], v92 offset:13344
	ds_read_b64 v[182:183], v92 offset:15616
	ds_read_b64 v[184:185], v92 offset:15648
	ds_read_b64 v[186:187], v92 offset:17920
	ds_read_b64 v[188:189], v92 offset:17952
	ds_read_b64 v[190:191], v92 offset:20224
	ds_read_b64 v[192:193], v92 offset:20256
	ds_read_b64 v[194:195], v92 offset:13376
	ds_read_b64 v[196:197], v92 offset:13408
	ds_read_b64 v[198:199], v92 offset:15680
	ds_read_b64 v[200:201], v92 offset:15712
	ds_read_b64 v[202:203], v92 offset:17984
	ds_read_b64 v[204:205], v92 offset:18016
	ds_read_b64 v[206:207], v92 offset:20288
	ds_read_b64 v[208:209], v92 offset:20320
	v_exp_f32_e32 v76, v76
	v_exp_f32_e32 v77, v77
	v_exp_f32_e32 v78, v78
	v_exp_f32_e32 v79, v79
	v_exp_f32_e32 v80, v80
	v_exp_f32_e32 v81, v81
	v_exp_f32_e32 v82, v82
	v_exp_f32_e32 v83, v83
	v_exp_f32_e32 v84, v84
	v_exp_f32_e32 v85, v85
	v_exp_f32_e32 v86, v86
	v_exp_f32_e32 v87, v87
	v_exp_f32_e32 v88, v88
	v_exp_f32_e32 v89, v89
	v_exp_f32_e32 v90, v90
	v_exp_f32_e32 v91, v91
	v_pk_add_f32 v[162:163], v[134:135], v[136:137]
	v_pk_add_f32 v[174:175], v[138:139], v[140:141]
	v_pk_add_f32 v[162:163], v[162:163], v[142:143]
	v_pk_add_f32 v[174:175], v[174:175], v[144:145]
	v_pk_add_f32 v[162:163], v[162:163], v[146:147]
	v_pk_add_f32 v[174:175], v[174:175], v[148:149]
	v_pk_add_f32 v[162:163], v[162:163], v[174:175]
	v_add_f32_e32 v154, v162, v163
	v_pk_add_f32 v[176:177], v[76:77], v[78:79]
	v_pk_add_f32 v[70:71], v[80:81], v[82:83]
	v_pk_add_f32 v[176:177], v[176:177], v[84:85]
	v_pk_add_f32 v[70:71], v[70:71], v[86:87]
	v_pk_add_f32 v[176:177], v[176:177], v[88:89]
	v_pk_add_f32 v[70:71], v[70:71], v[90:91]
	v_pk_add_f32 v[176:177], v[176:177], v[70:71]
	v_add_f32_e32 v155, v176, v177
	v_max_f32_e32 v156, v154, v155
	v_cmp_ngt_f32_e32 vcc, 0x45800000, v156
	v_cvt_pk_bf16_f32 v134, v134, v135
	v_cvt_pk_bf16_f32 v135, v136, v137
	v_cvt_pk_bf16_f32 v136, v138, v139
	v_cvt_pk_bf16_f32 v137, v140, v141
	s_and_b64 vcc, exec, vcc
	s_cbranch_vccnz .Lat3_slowq_2
	v_add_f32_e32 v125, v125, v154
	v_add_f32_e32 v124, v124, v155
	v_cvt_pk_bf16_f32 v142, v142, v143
	v_cvt_pk_bf16_f32 v143, v144, v145
	v_cvt_pk_bf16_f32 v144, v146, v147
	v_cvt_pk_bf16_f32 v145, v148, v149
	s_waitcnt lgkmcnt(8)
	v_mfma_f32_16x16x32_bf16 v[54:57], v[178:181], v[134:137], v[54:57]
	v_cvt_pk_bf16_f32 v76, v76, v77
	v_mfma_f32_16x16x32_bf16 v[58:61], v[182:185], v[134:137], v[58:61]
	v_cvt_pk_bf16_f32 v77, v78, v79
	v_mfma_f32_16x16x32_bf16 v[62:65], v[186:189], v[134:137], v[62:65]
	v_cvt_pk_bf16_f32 v78, v80, v81
	v_mfma_f32_16x16x32_bf16 v[66:69], v[190:193], v[134:137], v[66:69]
	v_cvt_pk_bf16_f32 v79, v82, v83
	s_waitcnt lgkmcnt(0)
	v_mfma_f32_16x16x32_bf16 v[54:57], v[194:197], v[142:145], v[54:57]
	v_cvt_pk_bf16_f32 v84, v84, v85
	v_mfma_f32_16x16x32_bf16 v[58:61], v[198:201], v[142:145], v[58:61]
	v_cvt_pk_bf16_f32 v85, v86, v87
	v_mfma_f32_16x16x32_bf16 v[62:65], v[202:205], v[142:145], v[62:65]
	v_cvt_pk_bf16_f32 v86, v88, v89
	v_mfma_f32_16x16x32_bf16 v[66:69], v[206:209], v[142:145], v[66:69]
	v_cvt_pk_bf16_f32 v87, v90, v91
	v_mfma_f32_16x16x32_bf16 v[4:7], v[178:181], v[76:79], v[4:7]
	v_mfma_f32_16x16x32_bf16 v[10:13], v[182:185], v[76:79], v[10:13]
	v_mfma_f32_16x16x32_bf16 v[14:17], v[186:189], v[76:79], v[14:17]
	v_mfma_f32_16x16x32_bf16 v[18:21], v[190:193], v[76:79], v[18:21]
	v_mfma_f32_16x16x32_bf16 v[4:7], v[194:197], v[84:87], v[4:7]
	v_mfma_f32_16x16x32_bf16 v[10:13], v[198:201], v[84:87], v[10:13]
	v_mfma_f32_16x16x32_bf16 v[14:17], v[202:205], v[84:87], v[14:17]
	v_mfma_f32_16x16x32_bf16 v[18:21], v[206:209], v[84:87], v[18:21]
	s_branch .Lat3_end_2
